# LCONV: conv weights hoisted out of the item loop, four tap rows loaded together under exec masks
# speedup vs baseline: 1.0152x; 1.0096x over previous
; __device__ __forceinline__ int opaque_bid() { int t; asm volatile("s_mov_b32 %0, %1" : "=s"(t) : "s"((int)blockIdx.x)); return t; }
; __device__ __forceinline__ unsigned pk2(float lo, float hi) { unsigned r; asm("v_cvt_pk_bf16_f32 %0, %1, %2" : "=v"(r) : "v"(lo), "v"(hi)); return r; }
; __device__ __forceinline__ float bflo(unsigned w) { return __uint_as_float(w << 16); }
; __device__ __forceinline__ float bfhi(unsigned w) { return __uint_as_float(w & 0xffff0000u); }
; __device__ __forceinline__ void lconv_phase(const bf16_t* REC, bf16_t* XR, const float* cw, const float* cbias, int tid, int G) {
; #pragma unroll 1
;     for (int it = opaque_bid() * 512 + tid; it < MT * 128; it += G * 512) { asm volatile("" : "+v"(it));
;         const int row = it >> 7, ch = (it & 127) * 8;
;         int pos, len; if (row < ML) { pos = row & (SEQ - 1); len = SEQ; } else { pos = (row - ML) & (CTXL - 1); len = CTXL; }
;         float acc[8];
;         { const f32x4 b0 = *(const f32x4*)(cbias + ch), b1 = *(const f32x4*)(cbias + ch + 4);
; #pragma unroll
;           for (int e = 0; e < 4; ++e) { acc[e] = b0[e]; acc[4 + e] = b1[e]; } }
; #pragma unroll
;         for (int k = 0; k < 4; ++k) { const int t = pos + k - 2;
;             if (t >= 0 && t < len) {
;                 const u32x4 v = *(const u32x4*)(REC + (size_t)(row + k - 2) * DM + ch);
;                 const f32x4 w0 = *(const f32x4*)(cw + k * DM + ch), w1 = *(const f32x4*)(cw + k * DM + ch + 4);
;                 acc[0] += w0[0] * bflo(v.x); acc[1] += w0[1] * bfhi(v.x); acc[2] += w0[2] * bflo(v.y); acc[3] += w0[3] * bfhi(v.y);
;                 acc[4] += w1[0] * bflo(v.z); acc[5] += w1[1] * bfhi(v.z); acc[6] += w1[2] * bflo(v.w); acc[7] += w1[3] * bfhi(v.w);
;             } }
;         u32x4 o; o.x = pk2(acc[0], acc[1]); o.y = pk2(acc[2], acc[3]); o.z = pk2(acc[4], acc[5]); o.w = pk2(acc[6], acc[7]);
;         *(u32x4*)(XR + (size_t)row * DM + ch) = o;
;     }
.LBB0_70:
	s_and_b64 vcc, exec, s[2:3]
	s_cbranch_vccz .LBB0_83
	v_mov_b32 v0, v220
	s_mov_b32 s2, s54
	s_nop 0
	s_mov_b32 s2, s54
	s_nop 0
	v_lshl_add_u32 v16, s2, 9, v0
	s_mov_b32 s2, 0x440000
	v_cmp_gt_i32_e32 vcc, s2, v16
	s_and_saveexec_b64 s[2:3], vcc
	s_cbranch_execz .LBB0_82
	v_readlane_b32 s6, v254, 41
	v_readlane_b32 s7, v254, 42
	s_load_dwordx2 s[8:9], s[6:7], 0xd8
	s_load_dwordx4 s[16:19], s[6:7], 0x70
	s_ashr_i32 s12, s61, 1
	s_waitcnt lgkmcnt(0)
	s_add_u32 s6, s8, 0xfe00000
	s_addc_u32 s7, s9, 0
	s_add_u32 s8, s8, 0x14200000
	s_addc_u32 s9, s9, 0
	s_ashr_i32 s13, s12, 31
	s_lshl_b64 s[10:11], s[12:13], 14
	s_add_u32 s10, s16, s10
	s_addc_u32 s11, s17, s11
	s_lshl_b64 s[12:13], s[12:13], 12
	s_add_u32 s12, s18, s12
	s_addc_u32 s13, s19, s13
	s_mov_b64 s[16:17], 0
	v_lshlrev_b32_e32 v0, 3, v16
	v_and_b32_e32 v9, 0x3f8, v0
	v_lshlrev_b32_e32 v48, 2, v9
	v_lshlrev_b32_e32 v10, 1, v9
	v_mov_b32_e32 v11, v49
	v_lshl_add_u64 v[12:13], s[10:11], 0, v[48:49]
	v_lshl_add_u64 v[14:15], s[6:7], 0, v[10:11]
	s_mov_b64 s[18:19], 0x1000
	global_load_dwordx4 v[60:63], v48, s[12:13]
	global_load_dwordx4 v[64:67], v48, s[12:13] offset:16
	global_load_dwordx4 v[68:71], v[12:13], off
	global_load_dwordx4 v[72:75], v[12:13], off offset:16
	v_lshl_add_u64 v[20:21], v[12:13], 0, s[18:19]
	s_mov_b64 s[18:19], 0x2000
	global_load_dwordx4 v[76:79], v[20:21], off
	global_load_dwordx4 v[80:83], v[20:21], off offset:16
	v_lshl_add_u64 v[22:23], v[12:13], 0, s[18:19]
	s_mov_b64 s[18:19], 0x3000
	global_load_dwordx4 v[84:87], v[22:23], off
	global_load_dwordx4 v[88:91], v[22:23], off offset:16
	v_lshl_add_u64 v[20:21], v[12:13], 0, s[18:19]
	s_nop 0
	global_load_dwordx4 v[92:95], v[20:21], off
	global_load_dwordx4 v[96:99], v[20:21], off offset:16
	s_waitcnt vmcnt(0)
	s_branch .LBB0_74
.LBB0_74:
	v_ashrrev_i32_e32 v8, 7, v16
	v_cmp_gt_i32_e32 vcc, 0x8000, v8
	v_mov_b32_e32 v18, 0x102
	v_mov_b32_e32 v19, 0x1002
	v_ashrrev_i32_e32 v9, 31, v8
	v_cndmask_b32_e32 v17, v231, v232, vcc
	v_cndmask_b32_e32 v18, v18, v19, vcc
	v_and_b32_e32 v17, v17, v8
	v_lshlrev_b64 v[20:21], 11, v[8:9]
	v_cmp_lt_u32_e32 vcc, 1, v17
	v_cmp_lt_u32_e64 s[40:41], v17, v18
	v_add_u32_e32 v19, 1, v17
	v_lshl_add_u64 v[22:23], v[14:15], 0, v[20:21]
	s_and_b64 s[6:7], vcc, s[40:41]
	v_cmp_ne_u32_e32 vcc, 0, v17
	v_cmp_lt_u32_e64 s[40:41], v19, v18
	v_add_u32_e32 v19, 2, v17
	v_add_u32_e32 v42, 3, v17
	s_and_b64 s[10:11], vcc, s[40:41]
	v_cmp_lt_u32_e64 s[12:13], v19, v18
	v_cmp_lt_u32_e64 s[18:19], v42, v18
	v_mov_b64_e32 v[24:25], 0
	v_mov_b64_e32 v[26:27], 0
	v_mov_b64_e32 v[28:29], 0
	v_mov_b64_e32 v[30:31], 0
	v_mov_b64_e32 v[32:33], 0
	v_mov_b64_e32 v[34:35], 0
	v_mov_b64_e32 v[36:37], 0
	v_mov_b64_e32 v[38:39], 0
	s_mov_b64 s[20:21], exec
	s_mov_b64 exec, s[6:7]
	global_load_dwordx4 v[24:27], v[22:23], off offset:-4096
	s_mov_b64 exec, s[10:11]
	global_load_dwordx4 v[28:31], v[22:23], off offset:-2048
	s_mov_b64 exec, s[12:13]
	global_load_dwordx4 v[32:35], v[22:23], off
	s_mov_b64 exec, s[18:19]
	global_load_dwordx4 v[36:39], v[22:23], off offset:2048
	s_mov_b64 exec, s[20:21]
	s_waitcnt vmcnt(3)
	v_lshlrev_b32_e32 v40, 16, v24
	v_and_b32_e32 v41, 0xffff0000, v24
	v_pk_fma_f32 v[4:5], v[68:69], v[40:41], v[60:61]
	v_lshlrev_b32_e32 v42, 16, v25
	v_and_b32_e32 v43, 0xffff0000, v25
	v_pk_fma_f32 v[6:7], v[70:71], v[42:43], v[62:63]
	v_lshlrev_b32_e32 v44, 16, v26
	v_and_b32_e32 v45, 0xffff0000, v26
	v_pk_fma_f32 v[0:1], v[72:73], v[44:45], v[64:65]
	v_lshlrev_b32_e32 v46, 16, v27
	v_and_b32_e32 v47, 0xffff0000, v27
	v_pk_fma_f32 v[2:3], v[74:75], v[46:47], v[66:67]
	s_waitcnt vmcnt(2)
	v_lshlrev_b32_e32 v40, 16, v28
	v_and_b32_e32 v41, 0xffff0000, v28
	v_pk_fma_f32 v[4:5], v[76:77], v[40:41], v[4:5]
	v_lshlrev_b32_e32 v42, 16, v29
	v_and_b32_e32 v43, 0xffff0000, v29
	v_pk_fma_f32 v[6:7], v[78:79], v[42:43], v[6:7]
	v_lshlrev_b32_e32 v44, 16, v30
	v_and_b32_e32 v45, 0xffff0000, v30
	v_pk_fma_f32 v[0:1], v[80:81], v[44:45], v[0:1]
	v_lshlrev_b32_e32 v46, 16, v31
	v_and_b32_e32 v47, 0xffff0000, v31
	v_pk_fma_f32 v[2:3], v[82:83], v[46:47], v[2:3]
	s_waitcnt vmcnt(1)
	v_lshlrev_b32_e32 v40, 16, v32
	v_and_b32_e32 v41, 0xffff0000, v32
	v_pk_fma_f32 v[4:5], v[84:85], v[40:41], v[4:5]
	v_lshlrev_b32_e32 v42, 16, v33
	v_and_b32_e32 v43, 0xffff0000, v33
	v_pk_fma_f32 v[6:7], v[86:87], v[42:43], v[6:7]
	v_lshlrev_b32_e32 v44, 16, v34
	v_and_b32_e32 v45, 0xffff0000, v34
	v_pk_fma_f32 v[0:1], v[88:89], v[44:45], v[0:1]
	v_lshlrev_b32_e32 v46, 16, v35
	v_and_b32_e32 v47, 0xffff0000, v35
	v_pk_fma_f32 v[2:3], v[90:91], v[46:47], v[2:3]
	s_waitcnt vmcnt(0)
	v_lshlrev_b32_e32 v40, 16, v36
	v_and_b32_e32 v41, 0xffff0000, v36
	v_pk_fma_f32 v[4:5], v[92:93], v[40:41], v[4:5]
	v_lshlrev_b32_e32 v42, 16, v37
	v_and_b32_e32 v43, 0xffff0000, v37
	v_pk_fma_f32 v[6:7], v[94:95], v[42:43], v[6:7]
	v_lshlrev_b32_e32 v44, 16, v38
	v_and_b32_e32 v45, 0xffff0000, v38
	v_pk_fma_f32 v[0:1], v[96:97], v[44:45], v[0:1]
	v_lshlrev_b32_e32 v46, 16, v39
	v_and_b32_e32 v47, 0xffff0000, v39
	v_pk_fma_f32 v[2:3], v[98:99], v[46:47], v[2:3]
	v_cvt_pk_bf16_f32 v4, v4, v5
	v_cvt_pk_bf16_f32 v5, v6, v7
	v_cvt_pk_bf16_f32 v6, v0, v1
	v_cvt_pk_bf16_f32 v7, v2, v3
	v_lshl_add_u64 v[0:1], s[8:9], 0, v[20:21]
	v_add_u32_e32 v16, s69, v16
	v_lshl_add_u64 v[0:1], v[0:1], 0, v[10:11]
	v_cmp_lt_i32_e32 vcc, 0x43ffff, v16
	global_store_dwordx4 v[0:1], v[4:7], off
	s_or_b64 s[16:17], vcc, s[16:17]
	s_andn2_b64 exec, exec, s[16:17]
	s_cbranch_execnz .LBB0_74
